# grid barrier leader path: per-XCD generation bumped before the leader's own buffer_inv acquire (shorter release critical path)
# speedup vs baseline: 1.0128x; 1.0128x over previous
; __device__ __forceinline__ unsigned xb_ld(unsigned* p)              { return __hip_atomic_load(p, __ATOMIC_RELAXED, __HIP_MEMORY_SCOPE_AGENT); }
; __device__ __forceinline__ unsigned xb_add(unsigned* p, unsigned v) { return __hip_atomic_fetch_add(p, v, __ATOMIC_RELAXED, __HIP_MEMORY_SCOPE_AGENT); }
; #define XB_SPIN(cond, bar) do { unsigned _sp = 0; while (cond) { __builtin_amdgcn_s_sleep(1); \
;     if ((++_sp & 255u) == 0u) { if (xb_ld(&(bar)[XB_TMO])) break; if (_sp > XB_SPIN_CAP) { atomicAdd(&(bar)[XB_TMO], 1u); break; } } } } while (0)
; __device__ __forceinline__ void xcd_barrier(const XcdBarrier& b) {
;     ...
;             else XB_SPIN(xb_ld(&bar[XB_TOPGEN]) == tg, bar);
;             __builtin_amdgcn_fence(__ATOMIC_ACQUIRE, "agent");
;             xb_add(&bar[XB_XGEN(b.x)], 1u);
;             asm volatile("s_waitcnt vmcnt(0)" ::: "memory");
.LBB0_176:
	s_or_b64 exec, exec, s[8:9]
	s_mov_b64 s[8:9], exec
	v_mbcnt_lo_u32_b32 v0, s8, 0
	v_mbcnt_hi_u32_b32 v0, s9, v0
	v_cmp_eq_u32_e32 vcc, 0, v0
	s_waitcnt vmcnt(0)
	s_and_saveexec_b64 s[12:13], vcc
	s_cbranch_execz .LBB0_178
	s_bcnt1_i32_b64 s3, s[8:9]
	v_mov_b32_e32 v0, 0x2000
	v_mov_b32_e32 v1, s3
	global_atomic_add v0, v1, s[6:7] offset:1024
.LBB0_178:
	s_or_b64 exec, exec, s[12:13]
	buffer_inv sc1
	s_waitcnt vmcnt(0)

; __device__ __forceinline__ unsigned xb_add(unsigned* p, unsigned v) { return __hip_atomic_fetch_add(p, v, __ATOMIC_RELAXED, __HIP_MEMORY_SCOPE_AGENT); }
; __device__ __forceinline__ void xcd_barrier(const XcdBarrier& b) {
;     ...
;             __builtin_amdgcn_fence(__ATOMIC_ACQUIRE, "agent");
;             xb_add(&bar[XB_XGEN(b.x)], 1u);
;             asm volatile("s_waitcnt vmcnt(0)" ::: "memory");
.LBB0_281:
	s_or_b64 exec, exec, s[8:9]
	s_mov_b64 s[8:9], exec
	v_mbcnt_lo_u32_b32 v0, s8, 0
	v_mbcnt_hi_u32_b32 v0, s9, v0
	v_cmp_eq_u32_e32 vcc, 0, v0
	s_waitcnt vmcnt(0)
	s_and_saveexec_b64 s[10:11], vcc
	s_cbranch_execz .LBB0_283
	s_bcnt1_i32_b64 s3, s[8:9]
	v_mov_b32_e32 v0, 0x2000
	v_mov_b32_e32 v1, s3
	global_atomic_add v0, v1, s[6:7] offset:1024
.LBB0_283:
	s_or_b64 exec, exec, s[10:11]
	buffer_inv sc1
	s_waitcnt vmcnt(0)

; __device__ __forceinline__ unsigned xb_add(unsigned* p, unsigned v) { return __hip_atomic_fetch_add(p, v, __ATOMIC_RELAXED, __HIP_MEMORY_SCOPE_AGENT); }
; __device__ __forceinline__ void xcd_barrier(const XcdBarrier& b) {
;     ...
;             __builtin_amdgcn_fence(__ATOMIC_ACQUIRE, "agent");
;             xb_add(&bar[XB_XGEN(b.x)], 1u);
;             asm volatile("s_waitcnt vmcnt(0)" ::: "memory");
.LBB0_1126:
	s_or_b64 exec, exec, s[8:9]
	s_mov_b64 s[8:9], exec
	v_mbcnt_lo_u32_b32 v0, s8, 0
	v_mbcnt_hi_u32_b32 v0, s9, v0
	v_cmp_eq_u32_e32 vcc, 0, v0
	s_waitcnt vmcnt(0)
	s_and_saveexec_b64 s[10:11], vcc
	s_cbranch_execz .LBB0_1128
	s_bcnt1_i32_b64 s8, s[8:9]
	v_mov_b32_e32 v0, 0x2000
	v_mov_b32_e32 v1, s8
	global_atomic_add v0, v1, s[6:7] offset:1024

; __device__ __forceinline__ unsigned xb_add(unsigned* p, unsigned v) { return __hip_atomic_fetch_add(p, v, __ATOMIC_RELAXED, __HIP_MEMORY_SCOPE_AGENT); }
; __device__ __forceinline__ void xcd_barrier(const XcdBarrier& b) {
;     ...
;             __builtin_amdgcn_fence(__ATOMIC_ACQUIRE, "agent");
;             xb_add(&bar[XB_XGEN(b.x)], 1u);
;             asm volatile("s_waitcnt vmcnt(0)" ::: "memory");
.LBB0_1211:
	s_or_b64 exec, exec, s[10:11]
	s_mov_b64 s[10:11], exec
	v_mbcnt_lo_u32_b32 v0, s10, 0
	v_mbcnt_hi_u32_b32 v0, s11, v0
	v_cmp_eq_u32_e32 vcc, 0, v0
	s_waitcnt vmcnt(0)
	s_and_saveexec_b64 s[12:13], vcc
	s_cbranch_execz .LBB0_1213
	s_bcnt1_i32_b64 s3, s[10:11]
	v_mov_b32_e32 v0, 0x2000
	v_mov_b32_e32 v1, s3
	global_atomic_add v0, v1, s[8:9] offset:1024
